# hand-written branch-chain (gate scaling) epilogue: two wave-uniform paths, SGPR-based addressing, second-half gate prefetch with counted waits, packed math
# speedup vs baseline: 1.0089x; 1.0089x over previous
.LBB0_355:
	v_readlane_b32 s0, v253, 25
	v_readlane_b32 s2, v253, 22
	s_lshl_b32 s1, s52, 2
	s_mul_i32 s0, s0, 12
	s_add_i32 s1, s2, s1
	s_add_i32 s0, s1, s0
	s_ashr_i32 s1, s0, 31
	s_lshl_b64 s[0:1], s[0:1], 17
	s_add_u32 s0, s50, s0
	s_addc_u32 s1, s51, s1
	s_add_u32 s2, s0, 0x80000
	s_addc_u32 s3, s1, 0
	v_lshlrev_b32_e32 v3, 3, v245
	v_lshl_add_u32 v2, v246, 7, v3
	v_lshlrev_b32_e32 v228, 1, v2
	s_cmp_eq_u32 s52, 2
	s_cbranch_scc1 .Lch_sub2
	global_load_dwordx4 v[132:135], v228, s[0:1]
	global_load_dwordx4 v[164:167], v228, s[2:3]
	s_add_u32 s0, s0, 0x2000
	s_addc_u32 s1, s1, 0
	s_add_u32 s2, s2, 0x2000
	s_addc_u32 s3, s3, 0
	global_load_dwordx4 v[136:139], v228, s[0:1]
	global_load_dwordx4 v[168:171], v228, s[2:3]
	s_add_u32 s0, s0, 0x2000
	s_addc_u32 s1, s1, 0
	s_add_u32 s2, s2, 0x2000
	s_addc_u32 s3, s3, 0
	global_load_dwordx4 v[140:143], v228, s[0:1]
	global_load_dwordx4 v[172:175], v228, s[2:3]
	s_add_u32 s0, s0, 0x2000
	s_addc_u32 s1, s1, 0
	s_add_u32 s2, s2, 0x2000
	s_addc_u32 s3, s3, 0
	global_load_dwordx4 v[144:147], v228, s[0:1]
	global_load_dwordx4 v[176:179], v228, s[2:3]
	s_add_u32 s0, s0, 0x2000
	s_addc_u32 s1, s1, 0
	s_add_u32 s2, s2, 0x2000
	s_addc_u32 s3, s3, 0
	global_load_dwordx4 v[148:151], v228, s[0:1]
	global_load_dwordx4 v[180:183], v228, s[2:3]
	s_add_u32 s0, s0, 0x2000
	s_addc_u32 s1, s1, 0
	s_add_u32 s2, s2, 0x2000
	s_addc_u32 s3, s3, 0
	global_load_dwordx4 v[152:155], v228, s[0:1]
	global_load_dwordx4 v[184:187], v228, s[2:3]
	s_add_u32 s0, s0, 0x2000
	s_addc_u32 s1, s1, 0
	s_add_u32 s2, s2, 0x2000
	s_addc_u32 s3, s3, 0
	global_load_dwordx4 v[156:159], v228, s[0:1]
	global_load_dwordx4 v[188:191], v228, s[2:3]
	s_add_u32 s0, s0, 0x2000
	s_addc_u32 s1, s1, 0
	s_add_u32 s2, s2, 0x2000
	s_addc_u32 s3, s3, 0
	global_load_dwordx4 v[160:163], v228, s[0:1]
	global_load_dwordx4 v[192:195], v228, s[2:3]
	s_add_u32 s0, s0, 0x2000
	s_addc_u32 s1, s1, 0
	s_add_u32 s2, s2, 0x2000
	s_addc_u32 s3, s3, 0
	s_waitcnt vmcnt(0)
	v_lshlrev_b32_e32 v208, 16, v132
	v_and_b32_e32 v209, 0xffff0000, v132
	v_lshlrev_b32_e32 v210, 16, v133
	v_and_b32_e32 v211, 0xffff0000, v133
	v_lshlrev_b32_e32 v212, 16, v134
	v_and_b32_e32 v213, 0xffff0000, v134
	v_lshlrev_b32_e32 v214, 16, v135
	v_and_b32_e32 v215, 0xffff0000, v135
	v_lshlrev_b32_e32 v236, 16, v164
	v_and_b32_e32 v237, 0xffff0000, v164
	v_lshlrev_b32_e32 v238, 16, v165
	v_and_b32_e32 v239, 0xffff0000, v165
	v_lshlrev_b32_e32 v230, 16, v166
	v_and_b32_e32 v231, 0xffff0000, v166
	v_lshlrev_b32_e32 v2, 16, v167
	v_and_b32_e32 v3, 0xffff0000, v167
	v_rcp_f32_e32 v236, v236
	v_rcp_f32_e32 v237, v237
	v_rcp_f32_e32 v238, v238
	v_rcp_f32_e32 v239, v239
	v_rcp_f32_e32 v230, v230
	v_rcp_f32_e32 v231, v231
	v_rcp_f32_e32 v2, v2
	v_rcp_f32_e32 v3, v3
	v_pk_mul_f32 v[236:237], v[236:237], v[208:209]
	v_pk_mul_f32 v[238:239], v[238:239], v[210:211]
	v_pk_mul_f32 v[230:231], v[230:231], v[212:213]
	v_pk_mul_f32 v[2:3], v[2:3], v[214:215]
	v_pk_mul_f32 v[128:129], v[128:129], v[236:237]
	v_pk_mul_f32 v[130:131], v[130:131], v[238:239]
	v_pk_mul_f32 v[124:125], v[124:125], v[230:231]
	v_pk_mul_f32 v[126:127], v[126:127], v[2:3]
	global_load_dwordx4 v[132:135], v228, s[0:1]
	global_load_dwordx4 v[164:167], v228, s[2:3]
	s_add_u32 s0, s0, 0x2000
	s_addc_u32 s1, s1, 0
	s_add_u32 s2, s2, 0x2000
	s_addc_u32 s3, s3, 0
	v_lshlrev_b32_e32 v208, 16, v136
	v_and_b32_e32 v209, 0xffff0000, v136
	v_lshlrev_b32_e32 v210, 16, v137
	v_and_b32_e32 v211, 0xffff0000, v137
	v_lshlrev_b32_e32 v212, 16, v138
	v_and_b32_e32 v213, 0xffff0000, v138
	v_lshlrev_b32_e32 v214, 16, v139
	v_and_b32_e32 v215, 0xffff0000, v139
	v_lshlrev_b32_e32 v236, 16, v168
	v_and_b32_e32 v237, 0xffff0000, v168
	v_lshlrev_b32_e32 v238, 16, v169
	v_and_b32_e32 v239, 0xffff0000, v169
	v_lshlrev_b32_e32 v230, 16, v170
	v_and_b32_e32 v231, 0xffff0000, v170
	v_lshlrev_b32_e32 v2, 16, v171
	v_and_b32_e32 v3, 0xffff0000, v171
	v_rcp_f32_e32 v236, v236
	v_rcp_f32_e32 v237, v237
	v_rcp_f32_e32 v238, v238
	v_rcp_f32_e32 v239, v239
	v_rcp_f32_e32 v230, v230
	v_rcp_f32_e32 v231, v231
	v_rcp_f32_e32 v2, v2
	v_rcp_f32_e32 v3, v3
	v_pk_mul_f32 v[236:237], v[236:237], v[208:209]
	v_pk_mul_f32 v[238:239], v[238:239], v[210:211]
	v_pk_mul_f32 v[230:231], v[230:231], v[212:213]
	v_pk_mul_f32 v[2:3], v[2:3], v[214:215]
	v_pk_mul_f32 v[96:97], v[96:97], v[236:237]
	v_pk_mul_f32 v[98:99], v[98:99], v[238:239]
	v_pk_mul_f32 v[92:93], v[92:93], v[230:231]
	v_pk_mul_f32 v[94:95], v[94:95], v[2:3]
	global_load_dwordx4 v[136:139], v228, s[0:1]
	global_load_dwordx4 v[168:171], v228, s[2:3]
	s_add_u32 s0, s0, 0x2000
	s_addc_u32 s1, s1, 0
	s_add_u32 s2, s2, 0x2000
	s_addc_u32 s3, s3, 0
	v_lshlrev_b32_e32 v208, 16, v140
	v_and_b32_e32 v209, 0xffff0000, v140
	v_lshlrev_b32_e32 v210, 16, v141
	v_and_b32_e32 v211, 0xffff0000, v141
	v_lshlrev_b32_e32 v212, 16, v142
	v_and_b32_e32 v213, 0xffff0000, v142
	v_lshlrev_b32_e32 v214, 16, v143
	v_and_b32_e32 v215, 0xffff0000, v143
	v_lshlrev_b32_e32 v236, 16, v172
	v_and_b32_e32 v237, 0xffff0000, v172
	v_lshlrev_b32_e32 v238, 16, v173
	v_and_b32_e32 v239, 0xffff0000, v173
	v_lshlrev_b32_e32 v230, 16, v174
	v_and_b32_e32 v231, 0xffff0000, v174
	v_lshlrev_b32_e32 v2, 16, v175
	v_and_b32_e32 v3, 0xffff0000, v175
	v_rcp_f32_e32 v236, v236
	v_rcp_f32_e32 v237, v237
	v_rcp_f32_e32 v238, v238
	v_rcp_f32_e32 v239, v239
	v_rcp_f32_e32 v230, v230
	v_rcp_f32_e32 v231, v231
	v_rcp_f32_e32 v2, v2
	v_rcp_f32_e32 v3, v3
	v_pk_mul_f32 v[236:237], v[236:237], v[208:209]
	v_pk_mul_f32 v[238:239], v[238:239], v[210:211]
	v_pk_mul_f32 v[230:231], v[230:231], v[212:213]
	v_pk_mul_f32 v[2:3], v[2:3], v[214:215]
	v_pk_mul_f32 v[120:121], v[120:121], v[236:237]
	v_pk_mul_f32 v[122:123], v[122:123], v[238:239]
	v_pk_mul_f32 v[116:117], v[116:117], v[230:231]
	v_pk_mul_f32 v[118:119], v[118:119], v[2:3]
	global_load_dwordx4 v[140:143], v228, s[0:1]
	global_load_dwordx4 v[172:175], v228, s[2:3]
	s_add_u32 s0, s0, 0x2000
	s_addc_u32 s1, s1, 0
	s_add_u32 s2, s2, 0x2000
	s_addc_u32 s3, s3, 0
	v_lshlrev_b32_e32 v208, 16, v144
	v_and_b32_e32 v209, 0xffff0000, v144
	v_lshlrev_b32_e32 v210, 16, v145
	v_and_b32_e32 v211, 0xffff0000, v145
	v_lshlrev_b32_e32 v212, 16, v146
	v_and_b32_e32 v213, 0xffff0000, v146
	v_lshlrev_b32_e32 v214, 16, v147
	v_and_b32_e32 v215, 0xffff0000, v147
	v_lshlrev_b32_e32 v236, 16, v176
	v_and_b32_e32 v237, 0xffff0000, v176
	v_lshlrev_b32_e32 v238, 16, v177
	v_and_b32_e32 v239, 0xffff0000, v177
	v_lshlrev_b32_e32 v230, 16, v178
	v_and_b32_e32 v231, 0xffff0000, v178
	v_lshlrev_b32_e32 v2, 16, v179
	v_and_b32_e32 v3, 0xffff0000, v179
	v_rcp_f32_e32 v236, v236
	v_rcp_f32_e32 v237, v237
	v_rcp_f32_e32 v238, v238
	v_rcp_f32_e32 v239, v239
	v_rcp_f32_e32 v230, v230
	v_rcp_f32_e32 v231, v231
	v_rcp_f32_e32 v2, v2
	v_rcp_f32_e32 v3, v3
	v_pk_mul_f32 v[236:237], v[236:237], v[208:209]
	v_pk_mul_f32 v[238:239], v[238:239], v[210:211]
	v_pk_mul_f32 v[230:231], v[230:231], v[212:213]
	v_pk_mul_f32 v[2:3], v[2:3], v[214:215]
	v_pk_mul_f32 v[88:89], v[88:89], v[236:237]
	v_pk_mul_f32 v[90:91], v[90:91], v[238:239]
	v_pk_mul_f32 v[84:85], v[84:85], v[230:231]
	v_pk_mul_f32 v[86:87], v[86:87], v[2:3]
	global_load_dwordx4 v[144:147], v228, s[0:1]
	global_load_dwordx4 v[176:179], v228, s[2:3]
	s_add_u32 s0, s0, 0x2000
	s_addc_u32 s1, s1, 0
	s_add_u32 s2, s2, 0x2000
	s_addc_u32 s3, s3, 0
	v_lshlrev_b32_e32 v208, 16, v148
	v_and_b32_e32 v209, 0xffff0000, v148
	v_lshlrev_b32_e32 v210, 16, v149
	v_and_b32_e32 v211, 0xffff0000, v149
	v_lshlrev_b32_e32 v212, 16, v150
	v_and_b32_e32 v213, 0xffff0000, v150
	v_lshlrev_b32_e32 v214, 16, v151
	v_and_b32_e32 v215, 0xffff0000, v151
	v_lshlrev_b32_e32 v236, 16, v180
	v_and_b32_e32 v237, 0xffff0000, v180
	v_lshlrev_b32_e32 v238, 16, v181
	v_and_b32_e32 v239, 0xffff0000, v181
	v_lshlrev_b32_e32 v230, 16, v182
	v_and_b32_e32 v231, 0xffff0000, v182
	v_lshlrev_b32_e32 v2, 16, v183
	v_and_b32_e32 v3, 0xffff0000, v183
	v_rcp_f32_e32 v236, v236
	v_rcp_f32_e32 v237, v237
	v_rcp_f32_e32 v238, v238
	v_rcp_f32_e32 v239, v239
	v_rcp_f32_e32 v230, v230
	v_rcp_f32_e32 v231, v231
	v_rcp_f32_e32 v2, v2
	v_rcp_f32_e32 v3, v3
	v_pk_mul_f32 v[236:237], v[236:237], v[208:209]
	v_pk_mul_f32 v[238:239], v[238:239], v[210:211]
	v_pk_mul_f32 v[230:231], v[230:231], v[212:213]
	v_pk_mul_f32 v[2:3], v[2:3], v[214:215]
	v_pk_mul_f32 v[112:113], v[112:113], v[236:237]
	v_pk_mul_f32 v[114:115], v[114:115], v[238:239]
	v_pk_mul_f32 v[108:109], v[108:109], v[230:231]
	v_pk_mul_f32 v[110:111], v[110:111], v[2:3]
	global_load_dwordx4 v[148:151], v228, s[0:1]
	global_load_dwordx4 v[180:183], v228, s[2:3]
	s_add_u32 s0, s0, 0x2000
	s_addc_u32 s1, s1, 0
	s_add_u32 s2, s2, 0x2000
	s_addc_u32 s3, s3, 0
	v_lshlrev_b32_e32 v208, 16, v152
	v_and_b32_e32 v209, 0xffff0000, v152
	v_lshlrev_b32_e32 v210, 16, v153
	v_and_b32_e32 v211, 0xffff0000, v153
	v_lshlrev_b32_e32 v212, 16, v154
	v_and_b32_e32 v213, 0xffff0000, v154
	v_lshlrev_b32_e32 v214, 16, v155
	v_and_b32_e32 v215, 0xffff0000, v155
	v_lshlrev_b32_e32 v236, 16, v184
	v_and_b32_e32 v237, 0xffff0000, v184
	v_lshlrev_b32_e32 v238, 16, v185
	v_and_b32_e32 v239, 0xffff0000, v185
	v_lshlrev_b32_e32 v230, 16, v186
	v_and_b32_e32 v231, 0xffff0000, v186
	v_lshlrev_b32_e32 v2, 16, v187
	v_and_b32_e32 v3, 0xffff0000, v187
	v_rcp_f32_e32 v236, v236
	v_rcp_f32_e32 v237, v237
	v_rcp_f32_e32 v238, v238
	v_rcp_f32_e32 v239, v239
	v_rcp_f32_e32 v230, v230
	v_rcp_f32_e32 v231, v231
	v_rcp_f32_e32 v2, v2
	v_rcp_f32_e32 v3, v3
	v_pk_mul_f32 v[236:237], v[236:237], v[208:209]
	v_pk_mul_f32 v[238:239], v[238:239], v[210:211]
	v_pk_mul_f32 v[230:231], v[230:231], v[212:213]
	v_pk_mul_f32 v[2:3], v[2:3], v[214:215]
	v_pk_mul_f32 v[80:81], v[80:81], v[236:237]
	v_pk_mul_f32 v[82:83], v[82:83], v[238:239]
	v_pk_mul_f32 v[76:77], v[76:77], v[230:231]
	v_pk_mul_f32 v[78:79], v[78:79], v[2:3]
	global_load_dwordx4 v[152:155], v228, s[0:1]
	global_load_dwordx4 v[184:187], v228, s[2:3]
	s_add_u32 s0, s0, 0x2000
	s_addc_u32 s1, s1, 0
	s_add_u32 s2, s2, 0x2000
	s_addc_u32 s3, s3, 0
	v_lshlrev_b32_e32 v208, 16, v156
	v_and_b32_e32 v209, 0xffff0000, v156
	v_lshlrev_b32_e32 v210, 16, v157
	v_and_b32_e32 v211, 0xffff0000, v157
	v_lshlrev_b32_e32 v212, 16, v158
	v_and_b32_e32 v213, 0xffff0000, v158
	v_lshlrev_b32_e32 v214, 16, v159
	v_and_b32_e32 v215, 0xffff0000, v159
	v_lshlrev_b32_e32 v236, 16, v188
	v_and_b32_e32 v237, 0xffff0000, v188
	v_lshlrev_b32_e32 v238, 16, v189
	v_and_b32_e32 v239, 0xffff0000, v189
	v_lshlrev_b32_e32 v230, 16, v190
	v_and_b32_e32 v231, 0xffff0000, v190
	v_lshlrev_b32_e32 v2, 16, v191
	v_and_b32_e32 v3, 0xffff0000, v191
	v_rcp_f32_e32 v236, v236
	v_rcp_f32_e32 v237, v237
	v_rcp_f32_e32 v238, v238
	v_rcp_f32_e32 v239, v239
	v_rcp_f32_e32 v230, v230
	v_rcp_f32_e32 v231, v231
	v_rcp_f32_e32 v2, v2
	v_rcp_f32_e32 v3, v3
	v_pk_mul_f32 v[236:237], v[236:237], v[208:209]
	v_pk_mul_f32 v[238:239], v[238:239], v[210:211]
	v_pk_mul_f32 v[230:231], v[230:231], v[212:213]
	v_pk_mul_f32 v[2:3], v[2:3], v[214:215]
	v_pk_mul_f32 v[104:105], v[104:105], v[236:237]
	v_pk_mul_f32 v[106:107], v[106:107], v[238:239]
	v_pk_mul_f32 v[100:101], v[100:101], v[230:231]
	v_pk_mul_f32 v[102:103], v[102:103], v[2:3]
	global_load_dwordx4 v[156:159], v228, s[0:1]
	global_load_dwordx4 v[188:191], v228, s[2:3]
	s_add_u32 s0, s0, 0x2000
	s_addc_u32 s1, s1, 0
	s_add_u32 s2, s2, 0x2000
	s_addc_u32 s3, s3, 0
	v_lshlrev_b32_e32 v208, 16, v160
	v_and_b32_e32 v209, 0xffff0000, v160
	v_lshlrev_b32_e32 v210, 16, v161
	v_and_b32_e32 v211, 0xffff0000, v161
	v_lshlrev_b32_e32 v212, 16, v162
	v_and_b32_e32 v213, 0xffff0000, v162
	v_lshlrev_b32_e32 v214, 16, v163
	v_and_b32_e32 v215, 0xffff0000, v163
	v_lshlrev_b32_e32 v236, 16, v192
	v_and_b32_e32 v237, 0xffff0000, v192
	v_lshlrev_b32_e32 v238, 16, v193
	v_and_b32_e32 v239, 0xffff0000, v193
	v_lshlrev_b32_e32 v230, 16, v194
	v_and_b32_e32 v231, 0xffff0000, v194
	v_lshlrev_b32_e32 v2, 16, v195
	v_and_b32_e32 v3, 0xffff0000, v195
	v_rcp_f32_e32 v236, v236
	v_rcp_f32_e32 v237, v237
	v_rcp_f32_e32 v238, v238
	v_rcp_f32_e32 v239, v239
	v_rcp_f32_e32 v230, v230
	v_rcp_f32_e32 v231, v231
	v_rcp_f32_e32 v2, v2
	v_rcp_f32_e32 v3, v3
	v_pk_mul_f32 v[236:237], v[236:237], v[208:209]
	v_pk_mul_f32 v[238:239], v[238:239], v[210:211]
	v_pk_mul_f32 v[230:231], v[230:231], v[212:213]
	v_pk_mul_f32 v[2:3], v[2:3], v[214:215]
	v_pk_mul_f32 v[72:73], v[72:73], v[236:237]
	v_pk_mul_f32 v[74:75], v[74:75], v[238:239]
	v_pk_mul_f32 v[68:69], v[68:69], v[230:231]
	v_pk_mul_f32 v[70:71], v[70:71], v[2:3]
	global_load_dwordx4 v[160:163], v228, s[0:1]
	global_load_dwordx4 v[192:195], v228, s[2:3]
	s_add_u32 s0, s0, 0x2000
	s_addc_u32 s1, s1, 0
	s_add_u32 s2, s2, 0x2000
	s_addc_u32 s3, s3, 0
	s_waitcnt vmcnt(14)
	v_lshlrev_b32_e32 v208, 16, v132
	v_and_b32_e32 v209, 0xffff0000, v132
	v_lshlrev_b32_e32 v210, 16, v133
	v_and_b32_e32 v211, 0xffff0000, v133
	v_lshlrev_b32_e32 v212, 16, v134
	v_and_b32_e32 v213, 0xffff0000, v134
	v_lshlrev_b32_e32 v214, 16, v135
	v_and_b32_e32 v215, 0xffff0000, v135
	v_lshlrev_b32_e32 v236, 16, v164
	v_and_b32_e32 v237, 0xffff0000, v164
	v_lshlrev_b32_e32 v238, 16, v165
	v_and_b32_e32 v239, 0xffff0000, v165
	v_lshlrev_b32_e32 v230, 16, v166
	v_and_b32_e32 v231, 0xffff0000, v166
	v_lshlrev_b32_e32 v2, 16, v167
	v_and_b32_e32 v3, 0xffff0000, v167
	v_rcp_f32_e32 v236, v236
	v_rcp_f32_e32 v237, v237
	v_rcp_f32_e32 v238, v238
	v_rcp_f32_e32 v239, v239
	v_rcp_f32_e32 v230, v230
	v_rcp_f32_e32 v231, v231
	v_rcp_f32_e32 v2, v2
	v_rcp_f32_e32 v3, v3
	v_pk_mul_f32 v[236:237], v[236:237], v[208:209]
	v_pk_mul_f32 v[238:239], v[238:239], v[210:211]
	v_pk_mul_f32 v[230:231], v[230:231], v[212:213]
	v_pk_mul_f32 v[2:3], v[2:3], v[214:215]
	v_pk_mul_f32 v[64:65], v[64:65], v[236:237]
	v_pk_mul_f32 v[66:67], v[66:67], v[238:239]
	v_pk_mul_f32 v[60:61], v[60:61], v[230:231]
	v_pk_mul_f32 v[62:63], v[62:63], v[2:3]
	s_waitcnt vmcnt(12)
	v_lshlrev_b32_e32 v208, 16, v136
	v_and_b32_e32 v209, 0xffff0000, v136
	v_lshlrev_b32_e32 v210, 16, v137
	v_and_b32_e32 v211, 0xffff0000, v137
	v_lshlrev_b32_e32 v212, 16, v138
	v_and_b32_e32 v213, 0xffff0000, v138
	v_lshlrev_b32_e32 v214, 16, v139
	v_and_b32_e32 v215, 0xffff0000, v139
	v_lshlrev_b32_e32 v236, 16, v168
	v_and_b32_e32 v237, 0xffff0000, v168
	v_lshlrev_b32_e32 v238, 16, v169
	v_and_b32_e32 v239, 0xffff0000, v169
	v_lshlrev_b32_e32 v230, 16, v170
	v_and_b32_e32 v231, 0xffff0000, v170
	v_lshlrev_b32_e32 v2, 16, v171
	v_and_b32_e32 v3, 0xffff0000, v171
	v_rcp_f32_e32 v236, v236
	v_rcp_f32_e32 v237, v237
	v_rcp_f32_e32 v238, v238
	v_rcp_f32_e32 v239, v239
	v_rcp_f32_e32 v230, v230
	v_rcp_f32_e32 v231, v231
	v_rcp_f32_e32 v2, v2
	v_rcp_f32_e32 v3, v3
	v_pk_mul_f32 v[236:237], v[236:237], v[208:209]
	v_pk_mul_f32 v[238:239], v[238:239], v[210:211]
	v_pk_mul_f32 v[230:231], v[230:231], v[212:213]
	v_pk_mul_f32 v[2:3], v[2:3], v[214:215]
	v_pk_mul_f32 v[32:33], v[32:33], v[236:237]
	v_pk_mul_f32 v[34:35], v[34:35], v[238:239]
	v_pk_mul_f32 v[28:29], v[28:29], v[230:231]
	v_pk_mul_f32 v[30:31], v[30:31], v[2:3]
	s_waitcnt vmcnt(10)
	v_lshlrev_b32_e32 v208, 16, v140
	v_and_b32_e32 v209, 0xffff0000, v140
	v_lshlrev_b32_e32 v210, 16, v141
	v_and_b32_e32 v211, 0xffff0000, v141
	v_lshlrev_b32_e32 v212, 16, v142
	v_and_b32_e32 v213, 0xffff0000, v142
	v_lshlrev_b32_e32 v214, 16, v143
	v_and_b32_e32 v215, 0xffff0000, v143
	v_lshlrev_b32_e32 v236, 16, v172
	v_and_b32_e32 v237, 0xffff0000, v172
	v_lshlrev_b32_e32 v238, 16, v173
	v_and_b32_e32 v239, 0xffff0000, v173
	v_lshlrev_b32_e32 v230, 16, v174
	v_and_b32_e32 v231, 0xffff0000, v174
	v_lshlrev_b32_e32 v2, 16, v175
	v_and_b32_e32 v3, 0xffff0000, v175
	v_rcp_f32_e32 v236, v236
	v_rcp_f32_e32 v237, v237
	v_rcp_f32_e32 v238, v238
	v_rcp_f32_e32 v239, v239
	v_rcp_f32_e32 v230, v230
	v_rcp_f32_e32 v231, v231
	v_rcp_f32_e32 v2, v2
	v_rcp_f32_e32 v3, v3
	v_pk_mul_f32 v[236:237], v[236:237], v[208:209]
	v_pk_mul_f32 v[238:239], v[238:239], v[210:211]
	v_pk_mul_f32 v[230:231], v[230:231], v[212:213]
	v_pk_mul_f32 v[2:3], v[2:3], v[214:215]
	v_pk_mul_f32 v[56:57], v[56:57], v[236:237]
	v_pk_mul_f32 v[58:59], v[58:59], v[238:239]
	v_pk_mul_f32 v[52:53], v[52:53], v[230:231]
	v_pk_mul_f32 v[54:55], v[54:55], v[2:3]
	s_waitcnt vmcnt(8)
	v_lshlrev_b32_e32 v208, 16, v144
	v_and_b32_e32 v209, 0xffff0000, v144
	v_lshlrev_b32_e32 v210, 16, v145
	v_and_b32_e32 v211, 0xffff0000, v145
	v_lshlrev_b32_e32 v212, 16, v146
	v_and_b32_e32 v213, 0xffff0000, v146
	v_lshlrev_b32_e32 v214, 16, v147
	v_and_b32_e32 v215, 0xffff0000, v147
	v_lshlrev_b32_e32 v236, 16, v176
	v_and_b32_e32 v237, 0xffff0000, v176
	v_lshlrev_b32_e32 v238, 16, v177
	v_and_b32_e32 v239, 0xffff0000, v177
	v_lshlrev_b32_e32 v230, 16, v178
	v_and_b32_e32 v231, 0xffff0000, v178
	v_lshlrev_b32_e32 v2, 16, v179
	v_and_b32_e32 v3, 0xffff0000, v179
	v_rcp_f32_e32 v236, v236
	v_rcp_f32_e32 v237, v237
	v_rcp_f32_e32 v238, v238
	v_rcp_f32_e32 v239, v239
	v_rcp_f32_e32 v230, v230
	v_rcp_f32_e32 v231, v231
	v_rcp_f32_e32 v2, v2
	v_rcp_f32_e32 v3, v3
	v_pk_mul_f32 v[236:237], v[236:237], v[208:209]
	v_pk_mul_f32 v[238:239], v[238:239], v[210:211]
	v_pk_mul_f32 v[230:231], v[230:231], v[212:213]
	v_pk_mul_f32 v[2:3], v[2:3], v[214:215]
	v_pk_mul_f32 v[24:25], v[24:25], v[236:237]
	v_pk_mul_f32 v[26:27], v[26:27], v[238:239]
	v_pk_mul_f32 v[20:21], v[20:21], v[230:231]
	v_pk_mul_f32 v[22:23], v[22:23], v[2:3]
	s_waitcnt vmcnt(6)
	v_lshlrev_b32_e32 v208, 16, v148
	v_and_b32_e32 v209, 0xffff0000, v148
	v_lshlrev_b32_e32 v210, 16, v149
	v_and_b32_e32 v211, 0xffff0000, v149
	v_lshlrev_b32_e32 v212, 16, v150
	v_and_b32_e32 v213, 0xffff0000, v150
	v_lshlrev_b32_e32 v214, 16, v151
	v_and_b32_e32 v215, 0xffff0000, v151
	v_lshlrev_b32_e32 v236, 16, v180
	v_and_b32_e32 v237, 0xffff0000, v180
	v_lshlrev_b32_e32 v238, 16, v181
	v_and_b32_e32 v239, 0xffff0000, v181
	v_lshlrev_b32_e32 v230, 16, v182
	v_and_b32_e32 v231, 0xffff0000, v182
	v_lshlrev_b32_e32 v2, 16, v183
	v_and_b32_e32 v3, 0xffff0000, v183
	v_rcp_f32_e32 v236, v236
	v_rcp_f32_e32 v237, v237
	v_rcp_f32_e32 v238, v238
	v_rcp_f32_e32 v239, v239
	v_rcp_f32_e32 v230, v230
	v_rcp_f32_e32 v231, v231
	v_rcp_f32_e32 v2, v2
	v_rcp_f32_e32 v3, v3
	v_pk_mul_f32 v[236:237], v[236:237], v[208:209]
	v_pk_mul_f32 v[238:239], v[238:239], v[210:211]
	v_pk_mul_f32 v[230:231], v[230:231], v[212:213]
	v_pk_mul_f32 v[2:3], v[2:3], v[214:215]
	v_pk_mul_f32 v[48:49], v[48:49], v[236:237]
	v_pk_mul_f32 v[50:51], v[50:51], v[238:239]
	v_pk_mul_f32 v[44:45], v[44:45], v[230:231]
	v_pk_mul_f32 v[46:47], v[46:47], v[2:3]
	s_waitcnt vmcnt(4)
	v_lshlrev_b32_e32 v208, 16, v152
	v_and_b32_e32 v209, 0xffff0000, v152
	v_lshlrev_b32_e32 v210, 16, v153
	v_and_b32_e32 v211, 0xffff0000, v153
	v_lshlrev_b32_e32 v212, 16, v154
	v_and_b32_e32 v213, 0xffff0000, v154
	v_lshlrev_b32_e32 v214, 16, v155
	v_and_b32_e32 v215, 0xffff0000, v155
	v_lshlrev_b32_e32 v236, 16, v184
	v_and_b32_e32 v237, 0xffff0000, v184
	v_lshlrev_b32_e32 v238, 16, v185
	v_and_b32_e32 v239, 0xffff0000, v185
	v_lshlrev_b32_e32 v230, 16, v186
	v_and_b32_e32 v231, 0xffff0000, v186
	v_lshlrev_b32_e32 v2, 16, v187
	v_and_b32_e32 v3, 0xffff0000, v187
	v_rcp_f32_e32 v236, v236
	v_rcp_f32_e32 v237, v237
	v_rcp_f32_e32 v238, v238
	v_rcp_f32_e32 v239, v239
	v_rcp_f32_e32 v230, v230
	v_rcp_f32_e32 v231, v231
	v_rcp_f32_e32 v2, v2
	v_rcp_f32_e32 v3, v3
	v_pk_mul_f32 v[236:237], v[236:237], v[208:209]
	v_pk_mul_f32 v[238:239], v[238:239], v[210:211]
	v_pk_mul_f32 v[230:231], v[230:231], v[212:213]
	v_pk_mul_f32 v[2:3], v[2:3], v[214:215]
	v_pk_mul_f32 v[16:17], v[16:17], v[236:237]
	v_pk_mul_f32 v[18:19], v[18:19], v[238:239]
	v_pk_mul_f32 v[12:13], v[12:13], v[230:231]
	v_pk_mul_f32 v[14:15], v[14:15], v[2:3]
	s_waitcnt vmcnt(2)
	v_lshlrev_b32_e32 v208, 16, v156
	v_and_b32_e32 v209, 0xffff0000, v156
	v_lshlrev_b32_e32 v210, 16, v157
	v_and_b32_e32 v211, 0xffff0000, v157
	v_lshlrev_b32_e32 v212, 16, v158
	v_and_b32_e32 v213, 0xffff0000, v158
	v_lshlrev_b32_e32 v214, 16, v159
	v_and_b32_e32 v215, 0xffff0000, v159
	v_lshlrev_b32_e32 v236, 16, v188
	v_and_b32_e32 v237, 0xffff0000, v188
	v_lshlrev_b32_e32 v238, 16, v189
	v_and_b32_e32 v239, 0xffff0000, v189
	v_lshlrev_b32_e32 v230, 16, v190
	v_and_b32_e32 v231, 0xffff0000, v190
	v_lshlrev_b32_e32 v2, 16, v191
	v_and_b32_e32 v3, 0xffff0000, v191
	v_rcp_f32_e32 v236, v236
	v_rcp_f32_e32 v237, v237
	v_rcp_f32_e32 v238, v238
	v_rcp_f32_e32 v239, v239
	v_rcp_f32_e32 v230, v230
	v_rcp_f32_e32 v231, v231
	v_rcp_f32_e32 v2, v2
	v_rcp_f32_e32 v3, v3
	v_pk_mul_f32 v[236:237], v[236:237], v[208:209]
	v_pk_mul_f32 v[238:239], v[238:239], v[210:211]
	v_pk_mul_f32 v[230:231], v[230:231], v[212:213]
	v_pk_mul_f32 v[2:3], v[2:3], v[214:215]
	v_pk_mul_f32 v[40:41], v[40:41], v[236:237]
	v_pk_mul_f32 v[42:43], v[42:43], v[238:239]
	v_pk_mul_f32 v[36:37], v[36:37], v[230:231]
	v_pk_mul_f32 v[38:39], v[38:39], v[2:3]
	s_waitcnt vmcnt(0)
	v_lshlrev_b32_e32 v208, 16, v160
	v_and_b32_e32 v209, 0xffff0000, v160
	v_lshlrev_b32_e32 v210, 16, v161
	v_and_b32_e32 v211, 0xffff0000, v161
	v_lshlrev_b32_e32 v212, 16, v162
	v_and_b32_e32 v213, 0xffff0000, v162
	v_lshlrev_b32_e32 v214, 16, v163
	v_and_b32_e32 v215, 0xffff0000, v163
	v_lshlrev_b32_e32 v236, 16, v192
	v_and_b32_e32 v237, 0xffff0000, v192
	v_lshlrev_b32_e32 v238, 16, v193
	v_and_b32_e32 v239, 0xffff0000, v193
	v_lshlrev_b32_e32 v230, 16, v194
	v_and_b32_e32 v231, 0xffff0000, v194
	v_lshlrev_b32_e32 v2, 16, v195
	v_and_b32_e32 v3, 0xffff0000, v195
	v_rcp_f32_e32 v236, v236
	v_rcp_f32_e32 v237, v237
	v_rcp_f32_e32 v238, v238
	v_rcp_f32_e32 v239, v239
	v_rcp_f32_e32 v230, v230
	v_rcp_f32_e32 v231, v231
	v_rcp_f32_e32 v2, v2
	v_rcp_f32_e32 v3, v3
	v_pk_mul_f32 v[236:237], v[236:237], v[208:209]
	v_pk_mul_f32 v[238:239], v[238:239], v[210:211]
	v_pk_mul_f32 v[230:231], v[230:231], v[212:213]
	v_pk_mul_f32 v[2:3], v[2:3], v[214:215]
	v_pk_mul_f32 v[8:9], v[8:9], v[236:237]
	v_pk_mul_f32 v[10:11], v[10:11], v[238:239]
	v_pk_mul_f32 v[4:5], v[4:5], v[230:231]
	v_pk_mul_f32 v[6:7], v[6:7], v[2:3]
	s_branch .Lch_done
.Lch_sub2:
	v_readlane_b32 s4, v253, 25
	s_nop 0
	s_lshl_b32 s4, s4, 8
	s_add_i32 s4, s4, s19
	s_ashr_i32 s5, s4, 31
	s_lshl_b64 s[4:5], s[4:5], 11
	s_add_u32 s4, s28, s4
	s_addc_u32 s5, s29, s5
	v_readlane_b32 s2, v253, 22
	s_nop 0
	s_lshl_b32 s2, s2, 9
	s_add_u32 s4, s4, s2
	s_addc_u32 s5, s5, 0
	s_lshl_b32 s2, s40, 1
	s_add_u32 s4, s4, s2
	s_addc_u32 s5, s5, 0
	v_lshlrev_b32_e32 v240, 11, v245
	v_lshl_add_u32 v240, v246, 4, v240
	global_load_dwordx4 v[132:135], v228, s[0:1]
	s_add_u32 s0, s0, 0x2000
	s_addc_u32 s1, s1, 0
	global_load_dwordx4 v[136:139], v228, s[0:1]
	s_add_u32 s0, s0, 0x2000
	s_addc_u32 s1, s1, 0
	global_load_dwordx4 v[140:143], v228, s[0:1]
	s_add_u32 s0, s0, 0x2000
	s_addc_u32 s1, s1, 0
	global_load_dwordx4 v[144:147], v228, s[0:1]
	s_add_u32 s0, s0, 0x2000
	s_addc_u32 s1, s1, 0
	global_load_dwordx4 v[148:151], v228, s[0:1]
	s_add_u32 s0, s0, 0x2000
	s_addc_u32 s1, s1, 0
	global_load_dwordx4 v[152:155], v228, s[0:1]
	s_add_u32 s0, s0, 0x2000
	s_addc_u32 s1, s1, 0
	global_load_dwordx4 v[156:159], v228, s[0:1]
	s_add_u32 s0, s0, 0x2000
	s_addc_u32 s1, s1, 0
	global_load_dwordx4 v[160:163], v228, s[0:1]
	s_add_u32 s0, s0, 0x2000
	s_addc_u32 s1, s1, 0
	s_waitcnt vmcnt(0)
	v_lshlrev_b32_e32 v208, 16, v132
	v_and_b32_e32 v209, 0xffff0000, v132
	v_lshlrev_b32_e32 v210, 16, v133
	v_and_b32_e32 v211, 0xffff0000, v133
	v_lshlrev_b32_e32 v212, 16, v134
	v_and_b32_e32 v213, 0xffff0000, v134
	v_lshlrev_b32_e32 v214, 16, v135
	v_and_b32_e32 v215, 0xffff0000, v135
	v_pk_mul_f32 v[236:237], v[128:129], v[208:209]
	v_pk_mul_f32 v[238:239], v[130:131], v[210:211]
	v_pk_mul_f32 v[230:231], v[124:125], v[212:213]
	v_pk_mul_f32 v[2:3], v[126:127], v[214:215]
	v_cvt_pk_bf16_f32 v208, v236, v237
	v_cvt_pk_bf16_f32 v209, v238, v239
	v_cvt_pk_bf16_f32 v210, v230, v231
	v_cvt_pk_bf16_f32 v211, v2, v3
	global_store_dwordx4 v240, v[208:211], s[4:5]
	global_load_dwordx4 v[132:135], v228, s[0:1]
	s_add_u32 s0, s0, 0x2000
	s_addc_u32 s1, s1, 0
	v_lshlrev_b32_e32 v208, 16, v136
	v_and_b32_e32 v209, 0xffff0000, v136
	v_lshlrev_b32_e32 v210, 16, v137
	v_and_b32_e32 v211, 0xffff0000, v137
	v_lshlrev_b32_e32 v212, 16, v138
	v_and_b32_e32 v213, 0xffff0000, v138
	v_lshlrev_b32_e32 v214, 16, v139
	v_and_b32_e32 v215, 0xffff0000, v139
	v_pk_mul_f32 v[236:237], v[96:97], v[208:209]
	v_pk_mul_f32 v[238:239], v[98:99], v[210:211]
	v_pk_mul_f32 v[230:231], v[92:93], v[212:213]
	v_pk_mul_f32 v[2:3], v[94:95], v[214:215]
	v_cvt_pk_bf16_f32 v208, v236, v237
	v_cvt_pk_bf16_f32 v209, v238, v239
	v_cvt_pk_bf16_f32 v210, v230, v231
	v_cvt_pk_bf16_f32 v211, v2, v3
	global_store_dwordx4 v240, v[208:211], s[4:5] offset:256
	s_add_u32 s4, s4, 0x8000
	s_addc_u32 s5, s5, 0
	global_load_dwordx4 v[136:139], v228, s[0:1]
	s_add_u32 s0, s0, 0x2000
	s_addc_u32 s1, s1, 0
	v_lshlrev_b32_e32 v208, 16, v140
	v_and_b32_e32 v209, 0xffff0000, v140
	v_lshlrev_b32_e32 v210, 16, v141
	v_and_b32_e32 v211, 0xffff0000, v141
	v_lshlrev_b32_e32 v212, 16, v142
	v_and_b32_e32 v213, 0xffff0000, v142
	v_lshlrev_b32_e32 v214, 16, v143
	v_and_b32_e32 v215, 0xffff0000, v143
	v_pk_mul_f32 v[236:237], v[120:121], v[208:209]
	v_pk_mul_f32 v[238:239], v[122:123], v[210:211]
	v_pk_mul_f32 v[230:231], v[116:117], v[212:213]
	v_pk_mul_f32 v[2:3], v[118:119], v[214:215]
	v_cvt_pk_bf16_f32 v208, v236, v237
	v_cvt_pk_bf16_f32 v209, v238, v239
	v_cvt_pk_bf16_f32 v210, v230, v231
	v_cvt_pk_bf16_f32 v211, v2, v3
	global_store_dwordx4 v240, v[208:211], s[4:5]
	global_load_dwordx4 v[140:143], v228, s[0:1]
	s_add_u32 s0, s0, 0x2000
	s_addc_u32 s1, s1, 0
	v_lshlrev_b32_e32 v208, 16, v144
	v_and_b32_e32 v209, 0xffff0000, v144
	v_lshlrev_b32_e32 v210, 16, v145
	v_and_b32_e32 v211, 0xffff0000, v145
	v_lshlrev_b32_e32 v212, 16, v146
	v_and_b32_e32 v213, 0xffff0000, v146
	v_lshlrev_b32_e32 v214, 16, v147
	v_and_b32_e32 v215, 0xffff0000, v147
	v_pk_mul_f32 v[236:237], v[88:89], v[208:209]
	v_pk_mul_f32 v[238:239], v[90:91], v[210:211]
	v_pk_mul_f32 v[230:231], v[84:85], v[212:213]
	v_pk_mul_f32 v[2:3], v[86:87], v[214:215]
	v_cvt_pk_bf16_f32 v208, v236, v237
	v_cvt_pk_bf16_f32 v209, v238, v239
	v_cvt_pk_bf16_f32 v210, v230, v231
	v_cvt_pk_bf16_f32 v211, v2, v3
	global_store_dwordx4 v240, v[208:211], s[4:5] offset:256
	s_add_u32 s4, s4, 0x8000
	s_addc_u32 s5, s5, 0
	global_load_dwordx4 v[144:147], v228, s[0:1]
	s_add_u32 s0, s0, 0x2000
	s_addc_u32 s1, s1, 0
	v_lshlrev_b32_e32 v208, 16, v148
	v_and_b32_e32 v209, 0xffff0000, v148
	v_lshlrev_b32_e32 v210, 16, v149
	v_and_b32_e32 v211, 0xffff0000, v149
	v_lshlrev_b32_e32 v212, 16, v150
	v_and_b32_e32 v213, 0xffff0000, v150
	v_lshlrev_b32_e32 v214, 16, v151
	v_and_b32_e32 v215, 0xffff0000, v151
	v_pk_mul_f32 v[236:237], v[112:113], v[208:209]
	v_pk_mul_f32 v[238:239], v[114:115], v[210:211]
	v_pk_mul_f32 v[230:231], v[108:109], v[212:213]
	v_pk_mul_f32 v[2:3], v[110:111], v[214:215]
	v_cvt_pk_bf16_f32 v208, v236, v237
	v_cvt_pk_bf16_f32 v209, v238, v239
	v_cvt_pk_bf16_f32 v210, v230, v231
	v_cvt_pk_bf16_f32 v211, v2, v3
	global_store_dwordx4 v240, v[208:211], s[4:5]
	global_load_dwordx4 v[148:151], v228, s[0:1]
	s_add_u32 s0, s0, 0x2000
	s_addc_u32 s1, s1, 0
	v_lshlrev_b32_e32 v208, 16, v152
	v_and_b32_e32 v209, 0xffff0000, v152
	v_lshlrev_b32_e32 v210, 16, v153
	v_and_b32_e32 v211, 0xffff0000, v153
	v_lshlrev_b32_e32 v212, 16, v154
	v_and_b32_e32 v213, 0xffff0000, v154
	v_lshlrev_b32_e32 v214, 16, v155
	v_and_b32_e32 v215, 0xffff0000, v155
	v_pk_mul_f32 v[236:237], v[80:81], v[208:209]
	v_pk_mul_f32 v[238:239], v[82:83], v[210:211]
	v_pk_mul_f32 v[230:231], v[76:77], v[212:213]
	v_pk_mul_f32 v[2:3], v[78:79], v[214:215]
	v_cvt_pk_bf16_f32 v208, v236, v237
	v_cvt_pk_bf16_f32 v209, v238, v239
	v_cvt_pk_bf16_f32 v210, v230, v231
	v_cvt_pk_bf16_f32 v211, v2, v3
	global_store_dwordx4 v240, v[208:211], s[4:5] offset:256
	s_add_u32 s4, s4, 0x8000
	s_addc_u32 s5, s5, 0
	global_load_dwordx4 v[152:155], v228, s[0:1]
	s_add_u32 s0, s0, 0x2000
	s_addc_u32 s1, s1, 0
	v_lshlrev_b32_e32 v208, 16, v156
	v_and_b32_e32 v209, 0xffff0000, v156
	v_lshlrev_b32_e32 v210, 16, v157
	v_and_b32_e32 v211, 0xffff0000, v157
	v_lshlrev_b32_e32 v212, 16, v158
	v_and_b32_e32 v213, 0xffff0000, v158
	v_lshlrev_b32_e32 v214, 16, v159
	v_and_b32_e32 v215, 0xffff0000, v159
	v_pk_mul_f32 v[236:237], v[104:105], v[208:209]
	v_pk_mul_f32 v[238:239], v[106:107], v[210:211]
	v_pk_mul_f32 v[230:231], v[100:101], v[212:213]
	v_pk_mul_f32 v[2:3], v[102:103], v[214:215]
	v_cvt_pk_bf16_f32 v208, v236, v237
	v_cvt_pk_bf16_f32 v209, v238, v239
	v_cvt_pk_bf16_f32 v210, v230, v231
	v_cvt_pk_bf16_f32 v211, v2, v3
	global_store_dwordx4 v240, v[208:211], s[4:5]
	global_load_dwordx4 v[156:159], v228, s[0:1]
	s_add_u32 s0, s0, 0x2000
	s_addc_u32 s1, s1, 0
	v_lshlrev_b32_e32 v208, 16, v160
	v_and_b32_e32 v209, 0xffff0000, v160
	v_lshlrev_b32_e32 v210, 16, v161
	v_and_b32_e32 v211, 0xffff0000, v161
	v_lshlrev_b32_e32 v212, 16, v162
	v_and_b32_e32 v213, 0xffff0000, v162
	v_lshlrev_b32_e32 v214, 16, v163
	v_and_b32_e32 v215, 0xffff0000, v163
	v_pk_mul_f32 v[236:237], v[72:73], v[208:209]
	v_pk_mul_f32 v[238:239], v[74:75], v[210:211]
	v_pk_mul_f32 v[230:231], v[68:69], v[212:213]
	v_pk_mul_f32 v[2:3], v[70:71], v[214:215]
	v_cvt_pk_bf16_f32 v208, v236, v237
	v_cvt_pk_bf16_f32 v209, v238, v239
	v_cvt_pk_bf16_f32 v210, v230, v231
	v_cvt_pk_bf16_f32 v211, v2, v3
	global_store_dwordx4 v240, v[208:211], s[4:5] offset:256
	s_add_u32 s4, s4, 0x28000
	s_addc_u32 s5, s5, 0
	global_load_dwordx4 v[160:163], v228, s[0:1]
	s_add_u32 s0, s0, 0x2000
	s_addc_u32 s1, s1, 0
	s_waitcnt vmcnt(14)
	v_lshlrev_b32_e32 v208, 16, v132
	v_and_b32_e32 v209, 0xffff0000, v132
	v_lshlrev_b32_e32 v210, 16, v133
	v_and_b32_e32 v211, 0xffff0000, v133
	v_lshlrev_b32_e32 v212, 16, v134
	v_and_b32_e32 v213, 0xffff0000, v134
	v_lshlrev_b32_e32 v214, 16, v135
	v_and_b32_e32 v215, 0xffff0000, v135
	v_pk_mul_f32 v[236:237], v[64:65], v[208:209]
	v_pk_mul_f32 v[238:239], v[66:67], v[210:211]
	v_pk_mul_f32 v[230:231], v[60:61], v[212:213]
	v_pk_mul_f32 v[2:3], v[62:63], v[214:215]
	v_cvt_pk_bf16_f32 v208, v236, v237
	v_cvt_pk_bf16_f32 v209, v238, v239
	v_cvt_pk_bf16_f32 v210, v230, v231
	v_cvt_pk_bf16_f32 v211, v2, v3
	global_store_dwordx4 v240, v[208:211], s[4:5]
	s_waitcnt vmcnt(13)
	v_lshlrev_b32_e32 v208, 16, v136
	v_and_b32_e32 v209, 0xffff0000, v136
	v_lshlrev_b32_e32 v210, 16, v137
	v_and_b32_e32 v211, 0xffff0000, v137
	v_lshlrev_b32_e32 v212, 16, v138
	v_and_b32_e32 v213, 0xffff0000, v138
	v_lshlrev_b32_e32 v214, 16, v139
	v_and_b32_e32 v215, 0xffff0000, v139
	v_pk_mul_f32 v[236:237], v[32:33], v[208:209]
	v_pk_mul_f32 v[238:239], v[34:35], v[210:211]
	v_pk_mul_f32 v[230:231], v[28:29], v[212:213]
	v_pk_mul_f32 v[2:3], v[30:31], v[214:215]
	v_cvt_pk_bf16_f32 v208, v236, v237
	v_cvt_pk_bf16_f32 v209, v238, v239
	v_cvt_pk_bf16_f32 v210, v230, v231
	v_cvt_pk_bf16_f32 v211, v2, v3
	global_store_dwordx4 v240, v[208:211], s[4:5] offset:256
	s_add_u32 s4, s4, 0x8000
	s_addc_u32 s5, s5, 0
	s_waitcnt vmcnt(12)
	v_lshlrev_b32_e32 v208, 16, v140
	v_and_b32_e32 v209, 0xffff0000, v140
	v_lshlrev_b32_e32 v210, 16, v141
	v_and_b32_e32 v211, 0xffff0000, v141
	v_lshlrev_b32_e32 v212, 16, v142
	v_and_b32_e32 v213, 0xffff0000, v142
	v_lshlrev_b32_e32 v214, 16, v143
	v_and_b32_e32 v215, 0xffff0000, v143
	v_pk_mul_f32 v[236:237], v[56:57], v[208:209]
	v_pk_mul_f32 v[238:239], v[58:59], v[210:211]
	v_pk_mul_f32 v[230:231], v[52:53], v[212:213]
	v_pk_mul_f32 v[2:3], v[54:55], v[214:215]
	v_cvt_pk_bf16_f32 v208, v236, v237
	v_cvt_pk_bf16_f32 v209, v238, v239
	v_cvt_pk_bf16_f32 v210, v230, v231
	v_cvt_pk_bf16_f32 v211, v2, v3
	global_store_dwordx4 v240, v[208:211], s[4:5]
	s_waitcnt vmcnt(11)
	v_lshlrev_b32_e32 v208, 16, v144
	v_and_b32_e32 v209, 0xffff0000, v144
	v_lshlrev_b32_e32 v210, 16, v145
	v_and_b32_e32 v211, 0xffff0000, v145
	v_lshlrev_b32_e32 v212, 16, v146
	v_and_b32_e32 v213, 0xffff0000, v146
	v_lshlrev_b32_e32 v214, 16, v147
	v_and_b32_e32 v215, 0xffff0000, v147
	v_pk_mul_f32 v[236:237], v[24:25], v[208:209]
	v_pk_mul_f32 v[238:239], v[26:27], v[210:211]
	v_pk_mul_f32 v[230:231], v[20:21], v[212:213]
	v_pk_mul_f32 v[2:3], v[22:23], v[214:215]
	v_cvt_pk_bf16_f32 v208, v236, v237
	v_cvt_pk_bf16_f32 v209, v238, v239
	v_cvt_pk_bf16_f32 v210, v230, v231
	v_cvt_pk_bf16_f32 v211, v2, v3
	global_store_dwordx4 v240, v[208:211], s[4:5] offset:256
	s_add_u32 s4, s4, 0x8000
	s_addc_u32 s5, s5, 0
	s_waitcnt vmcnt(10)
	v_lshlrev_b32_e32 v208, 16, v148
	v_and_b32_e32 v209, 0xffff0000, v148
	v_lshlrev_b32_e32 v210, 16, v149
	v_and_b32_e32 v211, 0xffff0000, v149
	v_lshlrev_b32_e32 v212, 16, v150
	v_and_b32_e32 v213, 0xffff0000, v150
	v_lshlrev_b32_e32 v214, 16, v151
	v_and_b32_e32 v215, 0xffff0000, v151
	v_pk_mul_f32 v[236:237], v[48:49], v[208:209]
	v_pk_mul_f32 v[238:239], v[50:51], v[210:211]
	v_pk_mul_f32 v[230:231], v[44:45], v[212:213]
	v_pk_mul_f32 v[2:3], v[46:47], v[214:215]
	v_cvt_pk_bf16_f32 v208, v236, v237
	v_cvt_pk_bf16_f32 v209, v238, v239
	v_cvt_pk_bf16_f32 v210, v230, v231
	v_cvt_pk_bf16_f32 v211, v2, v3
	global_store_dwordx4 v240, v[208:211], s[4:5]
	s_waitcnt vmcnt(9)
	v_lshlrev_b32_e32 v208, 16, v152
	v_and_b32_e32 v209, 0xffff0000, v152
	v_lshlrev_b32_e32 v210, 16, v153
	v_and_b32_e32 v211, 0xffff0000, v153
	v_lshlrev_b32_e32 v212, 16, v154
	v_and_b32_e32 v213, 0xffff0000, v154
	v_lshlrev_b32_e32 v214, 16, v155
	v_and_b32_e32 v215, 0xffff0000, v155
	v_pk_mul_f32 v[236:237], v[16:17], v[208:209]
	v_pk_mul_f32 v[238:239], v[18:19], v[210:211]
	v_pk_mul_f32 v[230:231], v[12:13], v[212:213]
	v_pk_mul_f32 v[2:3], v[14:15], v[214:215]
	v_cvt_pk_bf16_f32 v208, v236, v237
	v_cvt_pk_bf16_f32 v209, v238, v239
	v_cvt_pk_bf16_f32 v210, v230, v231
	v_cvt_pk_bf16_f32 v211, v2, v3
	global_store_dwordx4 v240, v[208:211], s[4:5] offset:256
	s_add_u32 s4, s4, 0x8000
	s_addc_u32 s5, s5, 0
	s_waitcnt vmcnt(8)
	v_lshlrev_b32_e32 v208, 16, v156
	v_and_b32_e32 v209, 0xffff0000, v156
	v_lshlrev_b32_e32 v210, 16, v157
	v_and_b32_e32 v211, 0xffff0000, v157
	v_lshlrev_b32_e32 v212, 16, v158
	v_and_b32_e32 v213, 0xffff0000, v158
	v_lshlrev_b32_e32 v214, 16, v159
	v_and_b32_e32 v215, 0xffff0000, v159
	v_pk_mul_f32 v[236:237], v[40:41], v[208:209]
	v_pk_mul_f32 v[238:239], v[42:43], v[210:211]
	v_pk_mul_f32 v[230:231], v[36:37], v[212:213]
	v_pk_mul_f32 v[2:3], v[38:39], v[214:215]
	v_cvt_pk_bf16_f32 v208, v236, v237
	v_cvt_pk_bf16_f32 v209, v238, v239
	v_cvt_pk_bf16_f32 v210, v230, v231
	v_cvt_pk_bf16_f32 v211, v2, v3
	global_store_dwordx4 v240, v[208:211], s[4:5]
	s_waitcnt vmcnt(7)
	v_lshlrev_b32_e32 v208, 16, v160
	v_and_b32_e32 v209, 0xffff0000, v160
	v_lshlrev_b32_e32 v210, 16, v161
	v_and_b32_e32 v211, 0xffff0000, v161
	v_lshlrev_b32_e32 v212, 16, v162
	v_and_b32_e32 v213, 0xffff0000, v162
	v_lshlrev_b32_e32 v214, 16, v163
	v_and_b32_e32 v215, 0xffff0000, v163
	v_pk_mul_f32 v[236:237], v[8:9], v[208:209]
	v_pk_mul_f32 v[238:239], v[10:11], v[210:211]
	v_pk_mul_f32 v[230:231], v[4:5], v[212:213]
	v_pk_mul_f32 v[2:3], v[6:7], v[214:215]
	v_cvt_pk_bf16_f32 v208, v236, v237
	v_cvt_pk_bf16_f32 v209, v238, v239
	v_cvt_pk_bf16_f32 v210, v230, v231
	v_cvt_pk_bf16_f32 v211, v2, v3
	global_store_dwordx4 v240, v[208:211], s[4:5] offset:256
.Lch_done:
	s_andn2_b64 vcc, exec, s[48:49]
	s_cbranch_vccnz .LBB0_346
.LBB0_452:
	s_cmp_lg_u32 s52, 2
	s_mov_b32 s97, 0xff800000
	s_cbranch_scc1 .LBB0_454
	v_mov_b32_e32 v2, v1
	v_mov_b32_e32 v3, v1
	v_mov_b32_e32 v0, v1
	v_mov_b64_e32 v[6:7], v[2:3]
	v_mov_b64_e32 v[10:11], v[2:3]
	v_mov_b64_e32 v[14:15], v[2:3]
	v_mov_b64_e32 v[18:19], v[2:3]
	v_mov_b64_e32 v[22:23], v[2:3]
	v_mov_b64_e32 v[26:27], v[2:3]
	v_mov_b64_e32 v[30:31], v[2:3]
	v_mov_b64_e32 v[34:35], v[2:3]
	v_mov_b64_e32 v[38:39], v[2:3]
	v_mov_b64_e32 v[42:43], v[2:3]
	v_mov_b64_e32 v[46:47], v[2:3]
	v_mov_b64_e32 v[50:51], v[2:3]
	v_mov_b64_e32 v[54:55], v[2:3]
	v_mov_b64_e32 v[58:59], v[2:3]
	v_mov_b64_e32 v[62:63], v[2:3]
	v_mov_b64_e32 v[66:67], v[2:3]
	v_mov_b64_e32 v[70:71], v[2:3]
	v_mov_b64_e32 v[74:75], v[2:3]
	v_mov_b64_e32 v[78:79], v[2:3]
	v_mov_b64_e32 v[82:83], v[2:3]
	v_mov_b64_e32 v[86:87], v[2:3]
	v_mov_b64_e32 v[90:91], v[2:3]
	v_mov_b64_e32 v[94:95], v[2:3]
	v_mov_b64_e32 v[98:99], v[2:3]
	v_mov_b64_e32 v[102:103], v[2:3]
	v_mov_b64_e32 v[106:107], v[2:3]
	v_mov_b64_e32 v[110:111], v[2:3]
	v_mov_b64_e32 v[114:115], v[2:3]
	v_mov_b64_e32 v[118:119], v[2:3]
	v_mov_b64_e32 v[122:123], v[2:3]
	v_mov_b64_e32 v[126:127], v[2:3]
	v_mov_b64_e32 v[130:131], v[2:3]
	v_mov_b64_e32 v[4:5], v[0:1]
	v_mov_b64_e32 v[8:9], v[0:1]
	v_mov_b64_e32 v[12:13], v[0:1]
	v_mov_b64_e32 v[16:17], v[0:1]
	v_mov_b64_e32 v[20:21], v[0:1]
	v_mov_b64_e32 v[24:25], v[0:1]
	v_mov_b64_e32 v[28:29], v[0:1]
	v_mov_b64_e32 v[32:33], v[0:1]
	v_mov_b64_e32 v[36:37], v[0:1]
	v_mov_b64_e32 v[40:41], v[0:1]
	v_mov_b64_e32 v[44:45], v[0:1]
	v_mov_b64_e32 v[48:49], v[0:1]
	v_mov_b64_e32 v[52:53], v[0:1]
	v_mov_b64_e32 v[56:57], v[0:1]
	v_mov_b64_e32 v[60:61], v[0:1]
	v_mov_b64_e32 v[64:65], v[0:1]
	v_mov_b64_e32 v[68:69], v[0:1]
	v_mov_b64_e32 v[72:73], v[0:1]
	v_mov_b64_e32 v[76:77], v[0:1]
	v_mov_b64_e32 v[80:81], v[0:1]
	v_mov_b64_e32 v[84:85], v[0:1]
	v_mov_b64_e32 v[88:89], v[0:1]
	v_mov_b64_e32 v[92:93], v[0:1]
	v_mov_b64_e32 v[96:97], v[0:1]
	v_mov_b64_e32 v[100:101], v[0:1]
	v_mov_b64_e32 v[104:105], v[0:1]
	v_mov_b64_e32 v[108:109], v[0:1]
	v_mov_b64_e32 v[112:113], v[0:1]
	v_mov_b64_e32 v[116:117], v[0:1]
	v_mov_b64_e32 v[120:121], v[0:1]
	v_mov_b64_e32 v[124:125], v[0:1]
	v_mov_b64_e32 v[128:129], v[0:1]
